# layer-1 in-projection fp32 column block epilogue: 64 serial rs-load/vmcnt(0)/mul/store steps batched into groups of up to 16 loads with counted waits (stores no longer waited for)
# speedup vs baseline: 1.0176x; 1.0083x over previous
; DI int opaque_tid() { int t = threadIdx.x; asm volatile("" : "+v"(t)); return t; }
; DI int crow(int i, int h) { return (i & 3) + 8 * (i >> 2) + 4 * h; }
; template <class F>
; DI void epi_each(const f32x16 (&acc)[2][2], int m0, int n0, F f) {
;   const int tid = opaque_tid(), lane = tid & 63, w = tid >> 6, wm = w >> 1, wn = w & 1, h = lane >> 5;
; #pragma unroll
;   for (int mt = 0; mt < 2; mt++)
; #pragma unroll
;     for (int nt = 0; nt < 2; nt++)
; #pragma unroll
;       for (int i = 0; i < 16; i++)
;         f(m0 + wm * 64 + mt * 32 + crow(i, h), n0 + wn * 64 + nt * 32 + (lane & 31), acc[mt][nt][i]);
; __global__ void __launch_bounds__(256, 2) fwd_megakernel(Params p) {
;     ...
;                  else if (cb == 1) epi_each(acc, m0, n0, [=](int m, int n, float v) { f[(long)m * 1024 + (n - 1024)] = v * rs[m]; });
.LBB0_1206:
	v_mov_b32_e32 v65, v202
	s_nop 0
	v_lshrrev_b32_e32 v66, 3, v65
	v_ashrrev_i32_e32 v64, 1, v65
	v_and_b32_e32 v66, 4, v66
	v_and_or_b32 v64, v64, s46, v66
	v_subrev_u32_e32 v64, s52, v64
	v_add_u32_e32 v64, s39, v64
	v_subrev_u32_e32 v68, 48, v64
	v_ashrrev_i32_e32 v69, 31, v68
	v_lshl_add_u64 v[70:71], v[68:69], 2, s[18:19]
	global_load_dword v228, v[70:71], off
	v_and_b32_e32 v65, 0x5f, v65
	v_or_b32_e32 v66, s20, v65
	v_ashrrev_i32_e32 v67, 31, v66
	v_lshl_add_u64 v[66:67], v[66:67], 2, s[14:15]
	v_subrev_u32_e32 v72, 47, v64
	v_lshlrev_b64 v[68:69], 12, v[68:69]
	v_ashrrev_i32_e32 v73, 31, v72
	v_lshl_add_u64 v[68:69], v[66:67], 0, v[68:69]
	v_lshl_add_u64 v[74:75], v[72:73], 2, s[18:19]
	v_lshlrev_b64 v[72:73], 12, v[72:73]
	v_lshl_add_u64 v[72:73], v[66:67], 0, v[72:73]
	v_subrev_u32_e32 v80, 45, v64
	v_ashrrev_i32_e32 v81, 31, v80
	v_lshl_add_u64 v[82:83], v[80:81], 2, s[18:19]
	v_subrev_u32_e32 v86, 40, v64
	v_lshlrev_b64 v[80:81], 12, v[80:81]
	v_ashrrev_i32_e32 v87, 31, v86
	v_lshl_add_u64 v[80:81], v[66:67], 0, v[80:81]
	v_lshl_add_u64 v[88:89], v[86:87], 2, s[18:19]
	v_subrev_u32_e32 v90, 39, v64
	v_lshlrev_b64 v[86:87], 12, v[86:87]
	v_ashrrev_i32_e32 v91, 31, v90
	v_lshl_add_u64 v[86:87], v[66:67], 0, v[86:87]
	v_lshl_add_u64 v[92:93], v[90:91], 2, s[18:19]
	v_subrev_u32_e32 v94, 38, v64
	v_lshlrev_b64 v[90:91], 12, v[90:91]
	v_ashrrev_i32_e32 v95, 31, v94
	v_lshl_add_u64 v[90:91], v[66:67], 0, v[90:91]
	v_lshl_add_u64 v[96:97], v[94:95], 2, s[18:19]
	v_subrev_u32_e32 v98, 37, v64
	v_lshlrev_b64 v[94:95], 12, v[94:95]
	v_ashrrev_i32_e32 v99, 31, v98
	v_lshl_add_u64 v[94:95], v[66:67], 0, v[94:95]
	v_lshl_add_u64 v[100:101], v[98:99], 2, s[18:19]
	v_subrev_u32_e32 v102, 32, v64
	v_lshlrev_b64 v[98:99], 12, v[98:99]
	v_ashrrev_i32_e32 v103, 31, v102
	v_lshl_add_u64 v[98:99], v[66:67], 0, v[98:99]
	v_lshl_add_u64 v[104:105], v[102:103], 2, s[18:19]
	v_subrev_u32_e32 v106, 31, v64
	v_lshlrev_b64 v[102:103], 12, v[102:103]
	v_ashrrev_i32_e32 v107, 31, v106
	v_lshl_add_u64 v[102:103], v[66:67], 0, v[102:103]
	v_lshl_add_u64 v[108:109], v[106:107], 2, s[18:19]
	v_subrev_u32_e32 v110, 30, v64
	v_lshlrev_b64 v[106:107], 12, v[106:107]
	v_ashrrev_i32_e32 v111, 31, v110
	v_lshl_add_u64 v[106:107], v[66:67], 0, v[106:107]
	v_lshl_add_u64 v[112:113], v[110:111], 2, s[18:19]
	v_subrev_u32_e32 v114, 29, v64
	v_lshlrev_b64 v[110:111], 12, v[110:111]
	v_ashrrev_i32_e32 v115, 31, v114
	v_lshl_add_u64 v[110:111], v[66:67], 0, v[110:111]
	v_lshl_add_u64 v[116:117], v[114:115], 2, s[18:19]
	v_subrev_u32_e32 v118, 24, v64
	v_lshlrev_b64 v[114:115], 12, v[114:115]
	v_ashrrev_i32_e32 v119, 31, v118
	v_lshl_add_u64 v[114:115], v[66:67], 0, v[114:115]
	v_lshl_add_u64 v[120:121], v[118:119], 2, s[18:19]
	v_subrev_u32_e32 v122, 23, v64
	v_lshlrev_b64 v[118:119], 12, v[118:119]
	v_ashrrev_i32_e32 v123, 31, v122
	v_lshl_add_u64 v[118:119], v[66:67], 0, v[118:119]
	v_lshl_add_u64 v[124:125], v[122:123], 2, s[18:19]
	v_subrev_u32_e32 v126, 22, v64
	v_lshlrev_b64 v[122:123], 12, v[122:123]
	v_ashrrev_i32_e32 v127, 31, v126
	v_lshl_add_u64 v[122:123], v[66:67], 0, v[122:123]
	v_lshl_add_u64 v[128:129], v[126:127], 2, s[18:19]
	v_subrev_u32_e32 v130, 21, v64
	v_lshlrev_b64 v[126:127], 12, v[126:127]
	v_ashrrev_i32_e32 v131, 31, v130
	v_lshl_add_u64 v[126:127], v[66:67], 0, v[126:127]
	v_lshl_add_u64 v[132:133], v[130:131], 2, s[18:19]
	v_lshlrev_b64 v[130:131], 12, v[130:131]
	v_lshl_add_u64 v[130:131], v[66:67], 0, v[130:131]
	s_waitcnt vmcnt(0)
	v_mul_f32_e32 v65, v48, v228
	global_store_dword v[68:69], v65, off offset:-4096
	global_load_dword v228, v[74:75], off
	v_subrev_u32_e32 v76, 46, v64
	v_ashrrev_i32_e32 v77, 31, v76
	v_lshl_add_u64 v[78:79], v[76:77], 2, s[18:19]
	v_lshlrev_b64 v[76:77], 12, v[76:77]
	v_lshl_add_u64 v[76:77], v[66:67], 0, v[76:77]
	s_waitcnt vmcnt(0)
	v_mul_f32_e32 v65, v49, v228
	global_store_dword v[72:73], v65, off offset:-4096
	global_load_dword v228, v[78:79], off
	global_load_dword v229, v[82:83], off
	global_load_dword v230, v[88:89], off
	global_load_dword v231, v[92:93], off
	global_load_dword v232, v[96:97], off
	global_load_dword v233, v[100:101], off
	global_load_dword v234, v[104:105], off
	global_load_dword v235, v[108:109], off
	global_load_dword v236, v[112:113], off
	global_load_dword v237, v[116:117], off
	global_load_dword v238, v[120:121], off
	global_load_dword v239, v[124:125], off
	global_load_dword v240, v[128:129], off
	global_load_dword v241, v[132:133], off
	global_load_dword v242, v[70:71], off
	global_load_dword v243, v[74:75], off
	s_waitcnt vmcnt(15)
	v_mul_f32_e32 v65, v50, v228
	global_store_dword v[76:77], v65, off offset:-4096
	s_waitcnt vmcnt(15)
	v_mul_f32_e32 v65, v51, v229
	global_store_dword v[80:81], v65, off offset:-4096
	s_waitcnt vmcnt(15)
	v_mul_f32_e32 v65, v52, v230
	global_store_dword v[86:87], v65, off offset:-4096
	s_waitcnt vmcnt(15)
	v_mul_f32_e32 v65, v53, v231
	global_store_dword v[90:91], v65, off offset:-4096
	s_waitcnt vmcnt(15)
	v_mul_f32_e32 v65, v54, v232
	global_store_dword v[94:95], v65, off offset:-4096
	s_waitcnt vmcnt(15)
	v_mul_f32_e32 v65, v55, v233
	global_store_dword v[98:99], v65, off offset:-4096
	s_waitcnt vmcnt(15)
	v_mul_f32_e32 v65, v56, v234
	global_store_dword v[102:103], v65, off offset:-4096
	s_waitcnt vmcnt(15)
	v_mul_f32_e32 v65, v57, v235
	global_store_dword v[106:107], v65, off offset:-4096
	s_waitcnt vmcnt(15)
	v_mul_f32_e32 v65, v58, v236
	global_store_dword v[110:111], v65, off offset:-4096
	s_waitcnt vmcnt(15)
	v_mul_f32_e32 v65, v59, v237
	global_store_dword v[114:115], v65, off offset:-4096
	s_waitcnt vmcnt(15)
; DI int opaque_tid() { int t = threadIdx.x; asm volatile("" : "+v"(t)); return t; }
; DI int crow(int i, int h) { return (i & 3) + 8 * (i >> 2) + 4 * h; }
; template <class F>
; DI void epi_each(const f32x16 (&acc)[2][2], int m0, int n0, F f) {
;   const int tid = opaque_tid(), lane = tid & 63, w = tid >> 6, wm = w >> 1, wn = w & 1, h = lane >> 5;
; #pragma unroll
;   for (int mt = 0; mt < 2; mt++)
; #pragma unroll
;     for (int nt = 0; nt < 2; nt++)
; #pragma unroll
;       for (int i = 0; i < 16; i++)
;         f(m0 + wm * 64 + mt * 32 + crow(i, h), n0 + wn * 64 + nt * 32 + (lane & 31), acc[mt][nt][i]);
; __global__ void __launch_bounds__(256, 2) fwd_megakernel(Params p) {
;     ...
;                  else if (cb == 1) epi_each(acc, m0, n0, [=](int m, int n, float v) { f[(long)m * 1024 + (n - 1024)] = v * rs[m]; });
	v_mul_f32_e32 v65, v60, v238
	global_store_dword v[118:119], v65, off offset:-4096
	s_waitcnt vmcnt(15)
	v_mul_f32_e32 v65, v61, v239
	global_store_dword v[122:123], v65, off offset:-4096
	s_waitcnt vmcnt(15)
	v_mul_f32_e32 v65, v62, v240
	global_store_dword v[126:127], v65, off offset:-4096
	s_waitcnt vmcnt(15)
	v_mul_f32_e32 v65, v63, v241
	global_store_dword v[130:131], v65, off offset:-4096
	s_waitcnt vmcnt(15)
	v_mul_f32_e32 v65, v32, v242
	global_store_dword v[68:69], v65, off offset:-3968
	v_add_u32_e32 v68, -16, v64
	v_ashrrev_i32_e32 v69, 31, v68
	v_lshl_add_u64 v[70:71], v[68:69], 2, s[18:19]
	v_lshlrev_b64 v[68:69], 12, v[68:69]
	v_lshl_add_u64 v[68:69], v[66:67], 0, v[68:69]
	s_waitcnt vmcnt(15)
	v_mul_f32_e32 v65, v33, v243
	global_store_dword v[72:73], v65, off offset:-3968
	global_load_dword v228, v[78:79], off
	global_load_dword v229, v[82:83], off
	global_load_dword v230, v[88:89], off
	global_load_dword v231, v[92:93], off
	global_load_dword v232, v[96:97], off
	global_load_dword v233, v[100:101], off
	global_load_dword v234, v[104:105], off
	global_load_dword v235, v[108:109], off
	global_load_dword v236, v[112:113], off
	global_load_dword v237, v[116:117], off
	global_load_dword v238, v[120:121], off
	global_load_dword v239, v[124:125], off
	global_load_dword v240, v[128:129], off
	global_load_dword v241, v[132:133], off
	global_load_dword v242, v[70:71], off
	v_add_u32_e32 v72, -15, v64
	v_ashrrev_i32_e32 v73, 31, v72
	v_lshl_add_u64 v[74:75], v[72:73], 2, s[18:19]
	v_lshlrev_b64 v[72:73], 12, v[72:73]
	v_lshl_add_u64 v[72:73], v[66:67], 0, v[72:73]
	s_waitcnt vmcnt(14)
	v_mul_f32_e32 v65, v34, v228
	global_store_dword v[76:77], v65, off offset:-3968
	v_add_u32_e32 v76, -14, v64
	v_ashrrev_i32_e32 v77, 31, v76
	v_lshl_add_u64 v[78:79], v[76:77], 2, s[18:19]
	v_lshlrev_b64 v[76:77], 12, v[76:77]
	v_lshl_add_u64 v[76:77], v[66:67], 0, v[76:77]
	s_waitcnt vmcnt(14)
	v_mul_f32_e32 v65, v35, v229
	global_store_dword v[80:81], v65, off offset:-3968
	v_add_u32_e32 v80, -13, v64
	v_ashrrev_i32_e32 v81, 31, v80
	v_lshl_add_u64 v[82:83], v[80:81], 2, s[18:19]
	v_lshlrev_b64 v[80:81], 12, v[80:81]
	v_lshl_add_u64 v[80:81], v[66:67], 0, v[80:81]
	s_waitcnt vmcnt(14)
	v_mul_f32_e32 v65, v36, v230
	global_store_dword v[86:87], v65, off offset:-3968
	v_add_u32_e32 v86, -8, v64
	v_ashrrev_i32_e32 v87, 31, v86
	v_lshl_add_u64 v[88:89], v[86:87], 2, s[18:19]
	v_lshlrev_b64 v[86:87], 12, v[86:87]
	v_lshl_add_u64 v[86:87], v[66:67], 0, v[86:87]
	s_waitcnt vmcnt(14)
	v_mul_f32_e32 v65, v37, v231
	global_store_dword v[90:91], v65, off offset:-3968
	v_add_u32_e32 v90, -7, v64
	v_ashrrev_i32_e32 v91, 31, v90
	v_lshl_add_u64 v[92:93], v[90:91], 2, s[18:19]
	v_lshlrev_b64 v[90:91], 12, v[90:91]
	v_lshl_add_u64 v[90:91], v[66:67], 0, v[90:91]
	s_waitcnt vmcnt(14)
	v_mul_f32_e32 v65, v38, v232
	global_store_dword v[94:95], v65, off offset:-3968
	v_add_u32_e32 v94, -6, v64
	v_ashrrev_i32_e32 v95, 31, v94
	v_lshl_add_u64 v[96:97], v[94:95], 2, s[18:19]
	v_lshlrev_b64 v[94:95], 12, v[94:95]
	v_lshl_add_u64 v[94:95], v[66:67], 0, v[94:95]
	s_waitcnt vmcnt(14)
	v_mul_f32_e32 v65, v39, v233
	global_store_dword v[98:99], v65, off offset:-3968
	v_add_u32_e32 v98, -5, v64
	v_ashrrev_i32_e32 v99, 31, v98
	v_lshl_add_u64 v[100:101], v[98:99], 2, s[18:19]
	v_lshlrev_b64 v[98:99], 12, v[98:99]
	v_lshl_add_u64 v[98:99], v[66:67], 0, v[98:99]
	v_add_u32_e32 v104, 1, v64
	v_ashrrev_i32_e32 v105, 31, v104
	s_waitcnt vmcnt(14)
	v_mul_f32_e32 v65, v40, v234
	global_store_dword v[102:103], v65, off offset:-3968
	v_lshl_add_u64 v[108:109], v[104:105], 2, s[18:19]
	v_lshlrev_b64 v[104:105], 12, v[104:105]
	v_lshl_add_u64 v[104:105], v[66:67], 0, v[104:105]
	s_waitcnt vmcnt(14)
	v_mul_f32_e32 v65, v41, v235
	global_store_dword v[106:107], v65, off offset:-3968
	s_waitcnt vmcnt(14)
	v_mul_f32_e32 v65, v42, v236
	global_store_dword v[110:111], v65, off offset:-3968
	v_add_u32_e32 v110, 2, v64
	v_ashrrev_i32_e32 v111, 31, v110
	v_lshl_add_u64 v[112:113], v[110:111], 2, s[18:19]
	v_lshlrev_b64 v[110:111], 12, v[110:111]
	v_lshl_add_u64 v[110:111], v[66:67], 0, v[110:111]
	s_waitcnt vmcnt(14)
	v_mul_f32_e32 v65, v43, v237
	global_store_dword v[114:115], v65, off offset:-3968
	v_add_u32_e32 v114, 3, v64
	v_ashrrev_i32_e32 v115, 31, v114
	v_lshl_add_u64 v[116:117], v[114:115], 2, s[18:19]
	v_lshlrev_b64 v[114:115], 12, v[114:115]
	v_lshl_add_u64 v[114:115], v[66:67], 0, v[114:115]
	s_waitcnt vmcnt(14)
	v_mul_f32_e32 v65, v44, v238
	global_store_dword v[118:119], v65, off offset:-3968
	v_add_u32_e32 v118, 8, v64
	v_ashrrev_i32_e32 v119, 31, v118
	v_lshl_add_u64 v[120:121], v[118:119], 2, s[18:19]
	v_lshlrev_b64 v[118:119], 12, v[118:119]
	v_lshl_add_u64 v[118:119], v[66:67], 0, v[118:119]
	s_waitcnt vmcnt(14)
	v_mul_f32_e32 v65, v45, v239
	global_store_dword v[122:123], v65, off offset:-3968
	v_add_u32_e32 v122, 9, v64
	v_ashrrev_i32_e32 v123, 31, v122
	v_lshl_add_u64 v[124:125], v[122:123], 2, s[18:19]
	v_lshlrev_b64 v[122:123], 12, v[122:123]
	v_lshl_add_u64 v[122:123], v[66:67], 0, v[122:123]
	s_waitcnt vmcnt(14)
; DI int opaque_tid() { int t = threadIdx.x; asm volatile("" : "+v"(t)); return t; }
; DI int crow(int i, int h) { return (i & 3) + 8 * (i >> 2) + 4 * h; }
; template <class F>
; DI void epi_each(const f32x16 (&acc)[2][2], int m0, int n0, F f) {
;   const int tid = opaque_tid(), lane = tid & 63, w = tid >> 6, wm = w >> 1, wn = w & 1, h = lane >> 5;
; #pragma unroll
;   for (int mt = 0; mt < 2; mt++)
; #pragma unroll
;     for (int nt = 0; nt < 2; nt++)
; #pragma unroll
;       for (int i = 0; i < 16; i++)
;         f(m0 + wm * 64 + mt * 32 + crow(i, h), n0 + wn * 64 + nt * 32 + (lane & 31), acc[mt][nt][i]);
; __global__ void __launch_bounds__(256, 2) fwd_megakernel(Params p) {
;     ...
;                  else if (cb == 1) epi_each(acc, m0, n0, [=](int m, int n, float v) { f[(long)m * 1024 + (n - 1024)] = v * rs[m]; });
	v_mul_f32_e32 v65, v46, v240
	global_store_dword v[126:127], v65, off offset:-3968
	v_add_u32_e32 v126, 10, v64
	v_ashrrev_i32_e32 v127, 31, v126
	v_lshl_add_u64 v[128:129], v[126:127], 2, s[18:19]
	v_lshlrev_b64 v[126:127], 12, v[126:127]
	v_lshl_add_u64 v[126:127], v[66:67], 0, v[126:127]
	s_waitcnt vmcnt(14)
	v_mul_f32_e32 v65, v47, v241
	global_store_dword v[130:131], v65, off offset:-3968
	s_waitcnt vmcnt(14)
	v_mul_f32_e32 v65, v16, v242
	global_store_dword v[68:69], v65, off offset:-4096
	global_load_dword v228, v[74:75], off
	global_load_dword v229, v[78:79], off
	global_load_dword v230, v[82:83], off
	global_load_dword v231, v[88:89], off
	global_load_dword v232, v[92:93], off
	global_load_dword v233, v[96:97], off
	global_load_dword v234, v[100:101], off
	s_waitcnt vmcnt(6)
	v_mul_f32_e32 v65, v17, v228
	global_store_dword v[72:73], v65, off offset:-4096
	s_waitcnt vmcnt(6)
	v_mul_f32_e32 v65, v18, v229
	global_store_dword v[76:77], v65, off offset:-4096
	s_waitcnt vmcnt(6)
	v_mul_f32_e32 v65, v19, v230
	global_store_dword v[80:81], v65, off offset:-4096
	s_waitcnt vmcnt(6)
	v_mul_f32_e32 v65, v20, v231
	global_store_dword v[86:87], v65, off offset:-4096
	s_waitcnt vmcnt(6)
	v_mul_f32_e32 v65, v21, v232
	global_store_dword v[90:91], v65, off offset:-4096
	s_waitcnt vmcnt(6)
	v_mul_f32_e32 v65, v22, v233
	global_store_dword v[94:95], v65, off offset:-4096
	v_ashrrev_i32_e32 v65, 31, v64
	v_lshl_add_u64 v[102:103], v[64:65], 2, s[18:19]
	v_lshlrev_b64 v[106:107], 12, v[64:65]
	v_lshl_add_u64 v[106:107], v[66:67], 0, v[106:107]
	v_add_u32_e32 v64, 11, v64
	s_waitcnt vmcnt(6)
	v_mul_f32_e32 v84, v23, v234
	global_store_dword v[98:99], v84, off offset:-4096
	global_load_dword v228, v[102:103], off
	global_load_dword v229, v[108:109], off
	global_load_dword v230, v[112:113], off
	global_load_dword v231, v[116:117], off
	global_load_dword v232, v[120:121], off
	global_load_dword v233, v[124:125], off
	global_load_dword v234, v[128:129], off
	s_waitcnt vmcnt(6)
	v_mul_f32_e32 v65, v24, v228
	global_store_dword v[106:107], v65, off offset:-4096
	s_waitcnt vmcnt(6)
	v_mul_f32_e32 v65, v25, v229
	global_store_dword v[104:105], v65, off offset:-4096
	s_waitcnt vmcnt(6)
	v_mul_f32_e32 v65, v26, v230
	global_store_dword v[110:111], v65, off offset:-4096
	s_waitcnt vmcnt(6)
	v_mul_f32_e32 v65, v27, v231
	global_store_dword v[114:115], v65, off offset:-4096
	s_waitcnt vmcnt(6)
	v_mul_f32_e32 v65, v28, v232
	global_store_dword v[118:119], v65, off offset:-4096
	s_waitcnt vmcnt(6)
	v_mul_f32_e32 v65, v29, v233
	global_store_dword v[122:123], v65, off offset:-4096
	v_ashrrev_i32_e32 v65, 31, v64
	v_lshl_add_u64 v[130:131], v[64:65], 2, s[18:19]
	v_lshlrev_b64 v[64:65], 12, v[64:65]
	v_lshl_add_u64 v[64:65], v[66:67], 0, v[64:65]
	s_waitcnt vmcnt(6)
	v_mul_f32_e32 v84, v30, v234
	global_store_dword v[126:127], v84, off offset:-4096
	global_load_dword v228, v[130:131], off
	global_load_dword v229, v[70:71], off
	global_load_dword v230, v[74:75], off
	global_load_dword v231, v[78:79], off
	global_load_dword v232, v[82:83], off
	global_load_dword v233, v[88:89], off
	global_load_dword v234, v[92:93], off
	global_load_dword v235, v[96:97], off
	global_load_dword v236, v[100:101], off
	global_load_dword v237, v[102:103], off
	global_load_dword v238, v[108:109], off
	global_load_dword v239, v[112:113], off
	global_load_dword v240, v[116:117], off
	global_load_dword v241, v[120:121], off
	global_load_dword v242, v[124:125], off
	global_load_dword v243, v[128:129], off
	s_waitcnt vmcnt(15)
	v_mul_f32_e32 v84, v31, v228
	global_store_dword v[64:65], v84, off offset:-4096
	s_waitcnt vmcnt(15)
	v_mul_f32_e32 v66, v0, v229
	global_store_dword v[68:69], v66, off offset:-3968
	s_waitcnt vmcnt(15)
	v_mul_f32_e32 v66, v1, v230
	global_store_dword v[72:73], v66, off offset:-3968
	s_waitcnt vmcnt(15)
	v_mul_f32_e32 v66, v2, v231
	global_store_dword v[76:77], v66, off offset:-3968
	s_waitcnt vmcnt(15)
	v_mul_f32_e32 v66, v3, v232
	global_store_dword v[80:81], v66, off offset:-3968
	s_waitcnt vmcnt(15)
	v_mul_f32_e32 v66, v4, v233
	global_store_dword v[86:87], v66, off offset:-3968
	s_waitcnt vmcnt(15)
	v_mul_f32_e32 v66, v5, v234
	global_store_dword v[90:91], v66, off offset:-3968
	s_waitcnt vmcnt(15)
	v_mul_f32_e32 v66, v6, v235
	global_store_dword v[94:95], v66, off offset:-3968
	s_waitcnt vmcnt(15)
	v_mul_f32_e32 v66, v7, v236
	global_store_dword v[98:99], v66, off offset:-3968
	s_waitcnt vmcnt(15)
	v_mul_f32_e32 v66, v8, v237
	global_store_dword v[106:107], v66, off offset:-3968
	s_waitcnt vmcnt(15)
	v_mul_f32_e32 v66, v9, v238
	global_store_dword v[104:105], v66, off offset:-3968
	s_waitcnt vmcnt(15)
	v_mul_f32_e32 v66, v10, v239
	global_store_dword v[110:111], v66, off offset:-3968
	s_waitcnt vmcnt(15)
	v_mul_f32_e32 v66, v11, v240
	global_store_dword v[114:115], v66, off offset:-3968
	s_waitcnt vmcnt(15)
	v_mul_f32_e32 v66, v12, v241
	global_store_dword v[118:119], v66, off offset:-3968
	s_waitcnt vmcnt(15)
	v_mul_f32_e32 v66, v13, v242
	global_store_dword v[122:123], v66, off offset:-3968
	s_waitcnt vmcnt(15)
	v_mul_f32_e32 v66, v14, v243
	global_store_dword v[126:127], v66, off offset:-3968
	global_load_dword v228, v[130:131], off
	s_waitcnt vmcnt(0)
	v_mul_f32_e32 v66, v15, v228
	global_store_dword v[64:65], v66, off offset:-3968
